# static priority raise for waves 4-7 while a mixer item runs (reset at each dequeue), on top of the DPP wave_sum version
# baseline (speedup 1.0000x reference)
; #define LAS __attribute__((address_space(3)))
; __device__ __forceinline__ void sb_unit(LAS unsigned char* lds, const bf16* PROJ, bf16* MIX, int b, int h, int jq, int tid) {
;     const int lane = tid & 63, wid = __builtin_amdgcn_readfirstlane(tid >> 6), r32 = lane & 31, hi = lane >> 5;
;     const size_t rowbase = (size_t)b * SEQ; const int q0 = 256 * jq;
;     const bf16* Kg = PROJ + rowbase * NPROJ + 1536 + h * 64; const bf16* Vg = PROJ + rowbase * NPROJ + 2048 + h * 64;
;     const bf16* Qp = PROJ + (rowbase + q0 + 32 * wid + r32) * NPROJ + 1024 + h * 64;
;     bf16x8 qr[4];
; #pragma unroll
;     for (int d0 = 0; d0 < 4; ++d0) qr[d0] = *(const bf16x8*)(Qp + 16 * d0 + 8 * hi);
;     const int NT = 4 * jq + 4;
;     u32x4 kr, vr, kr1, vr1; tile_load(Kg, Vg, 64 * (NT - 1), tid, kr, vr); tile_load(Kg, Vg, 64 * (NT - 2), tid, kr1, vr1);
;     tile_store(lds, 0, tid, kr, vr); tile_store(lds, TILEB, tid, kr1, vr1);
;     __syncthreads();
;     f32x16 o[2];
; #pragma unroll
;     for (int r = 0; r < 16; ++r) { o[0][r] = 0.f; o[1][r] = 0.f; }
;     float carry = 0.f; const int Q0 = q0 + 32 * wid, qpos = Q0 + r32;
; __global__ void __launch_bounds__(NTHREADS, 2) fwd_megakernel(Params p_) {
;     ...
;             for (;;) {
;                 if (tid == 0) *qslot = __hip_atomic_fetch_add(qctr, 1u, __ATOMIC_RELAXED, __HIP_MEMORY_SCOPE_AGENT);
;                 __syncthreads();
;                 const int idx = __builtin_amdgcn_readfirstlane((int)*qslot);
;                 __syncthreads();
;                 if (idx >= total) break;
;                 int tq_; asm volatile("v_mov_b32 %0, %1" : "=v"(tq_) : "v"(tid));
;                 const int tq = tq_;
;                 if (even) {
;                     if (idx < 512) { const int j = 7 - (idx >> 6), bh = idx & 63; mx::moba_unit(lds, PROJ, MIX, bh >> 3, bh & 7, j, tq); }
;                     else mx::conv_item(lds, PROJ, MIX, p->conv_w + (size_t)li * 31 * 512, p->conv_b + li * 512, p->conv_ln_g + li * 512, p->conv_ln_b + li * 512, idx - 512, tq);
;                 } else {
;                     if (idx < 128) mx::sgu_item(lds, PROJ, MIX, p->sgu_ln_g + li * 512, p->sgu_ln_b + li * 512, p->sgu_w + (size_t)li * 4 * 128 * 128, p->sgu_b + li * 4 * 128, idx, tq);
;                     else { const int u = idx - 128, jq = 7 - (u >> 6), bh = u & 63; mx::sb_unit(lds, PROJ, MIX, bh >> 3, bh & 7, jq, tq); }
.LBB0_326:
	s_or_b64 exec, exec, s[0:1]
	s_setprio 0
	v_mov_b32_e32 v0, s76
	s_waitcnt vmcnt(0) lgkmcnt(0)
	s_barrier
	ds_read_b32 v0, v0
	s_mov_b64 s[0:1], -1
	s_waitcnt lgkmcnt(0)
	s_barrier
	v_readfirstlane_b32 s24, v0
	s_cmp_ge_i32 s24, s13
	s_cbranch_scc1 .LBB0_321
	v_readfirstlane_b32 s100, v236
	s_bitcmp1_b32 s100, 8
	s_cbranch_scc0 .Lprio_skip
	s_setprio 1
.Lprio_skip:
	s_and_b64 vcc, exec, s[92:93]
	v_mov_b32 v200, v236
	s_cbranch_vccz .LBB0_367
	s_cmpk_gt_i32 s24, 0x7f
	s_cbranch_scc0 .LBB0_357
	s_add_i32 s0, s24, 0xffffff80
	s_lshr_b32 s4, s0, 6
	v_readfirstlane_b32 s0, v200
	s_ashr_i32 s5, s0, 6
	s_lshl_b32 s0, s24, 8
	s_sub_i32 s6, 7, s4
	s_and_b32 s0, s0, 0x3800
	s_lshl_b32 s7, s6, 8
	s_mul_i32 s1, s0, 0x1400
	s_add_u32 s2, s84, s1
	s_addc_u32 s3, s85, 0
	s_lshl_b32 s1, s24, 6
	s_and_b32 s10, s1, 0x1c0
	s_ashr_i32 s1, s7, 31
	s_add_u32 s0, s7, s0
	v_and_b32_e32 v5, 31, v200
	s_addc_u32 s1, s1, 0
	s_lshl_b32 s8, s5, 5
	s_ashr_i32 s9, s8, 31
	v_or_b32_e32 v2, s0, v5
	v_mov_b32_e32 v3, s1
	v_lshl_add_u64 v[202:203], v[2:3], 0, s[8:9]
	v_mov_b64_e32 v[2:3], s[84:85]
	v_mad_u64_u32 v[2:3], s[0:1], v202, s40, v[2:3]
	s_lshl_b32 s82, s10, 1
	v_bfe_u32 v4, v200, 5, 1
	v_mad_i32_i24 v3, v203, s40, v3
	s_add_u32 s0, s2, s82
	v_lshl_add_u64 v[2:3], v[2:3], 0, s[82:83]
	v_lshlrev_b32_e32 v0, 4, v4
	s_addc_u32 s1, s3, 0
	v_lshl_add_u64 v[2:3], v[2:3], 0, v[0:1]
	s_add_u32 s2, s0, 0x1000
	global_load_dwordx4 v[176:179], v[2:3], off offset:2048
	global_load_dwordx4 v[180:183], v[2:3], off offset:2080
	global_load_dwordx4 v[184:187], v[2:3], off offset:2112
	global_load_dwordx4 v[188:191], v[2:3], off offset:2144
	s_addc_u32 s3, s1, 0
	s_or_b32 s9, s7, 0xc0
	v_ashrrev_i32_e32 v201, 3, v200
	v_lshlrev_b32_e32 v2, 3, v200
	v_add_u32_e32 v12, s9, v201
	v_mov_b64_e32 v[6:7], s[0:1]
	v_and_b32_e32 v2, 56, v2
	v_mad_i64_i32 v[8:9], s[10:11], v12, s40, v[6:7]
	v_lshlrev_b32_e32 v2, 1, v2
	v_mov_b32_e32 v3, v1
	v_lshl_add_u64 v[8:9], v[8:9], 0, v[2:3]
	v_mov_b64_e32 v[10:11], s[2:3]
	global_load_dwordx4 v[192:195], v[8:9], off offset:3072
	v_mad_i64_i32 v[8:9], s[10:11], v12, s40, v[10:11]
	v_lshl_add_u64 v[8:9], v[8:9], 0, v[2:3]
	global_load_dwordx4 v[196:199], v[8:9], off
	v_add_u32_e32 v8, s7, v201
	v_add_u32_e32 v12, 0x80, v8
	v_mad_i64_i32 v[6:7], s[10:11], v12, s40, v[6:7]
	v_lshl_add_u64 v[6:7], v[6:7], 0, v[2:3]
	v_mad_i64_i32 v[10:11], s[10:11], v12, s40, v[10:11]
	global_load_dwordx4 v[6:9], v[6:7], off offset:3072
	v_lshl_add_u64 v[10:11], v[10:11], 0, v[2:3]
	global_load_dwordx4 v[10:13], v[10:11], off
	s_add_i32 s25, s8, s7
	s_or_b32 s92, s25, 30
	v_lshlrev_b32_e32 v14, 4, v200
	s_cmp_le_i32 s9, s92
	v_mul_lo_u32 v3, v201, s43
	v_and_b32_e32 v14, 0x70, v14
	s_cselect_b64 s[16:17], -1, 0
	v_add3_u32 v210, 0, v3, v14
	s_mov_b64 s[8:9], -1
	s_and_b64 vcc, exec, s[16:17]
	s_waitcnt vmcnt(3)
	ds_write_b128 v210, v[192:195]
	s_waitcnt vmcnt(2)
	ds_write_b128 v210, v[196:199] offset:27648
	s_waitcnt vmcnt(1)
	ds_write_b128 v210, v[6:9] offset:9216
	s_waitcnt vmcnt(0)
	ds_write_b128 v210, v[10:13] offset:36864
	s_waitcnt lgkmcnt(0)
	s_barrier
	s_cbranch_vccnz .LBB0_331
	v_lshlrev_b32_e32 v6, 4, v4
	s_mov_b64 s[8:9], 0
